# speedup vs baseline: 1.0125x; 1.0125x over previous
; __device__ __forceinline__ void convert_items(KArgsF a, LAS unsigned char* lds, int first, int last, int first2, int last2, int w, int NW, int wave, int lane) {
;     ...
;     const int n1 = last - first, ntot = n1 + (last2 - first2);
; #pragma unroll 1
;     for (int iq = w; iq < ntot; iq += NW) {
;         const int it = iq < n1 ? first + iq : first2 + (iq - n1);
; __global__ void __launch_bounds__(NTHREADS, 2) hymba_fwd(Args a_unused) {
;     ...
;             if (l == 0 && (k == 0 || k == 4)) {
;                 const int nun = (MT / 256) * (g.N / 256), fi = nun % G;
;                 constexpr int DN0 = CV_IN + CV_OUT + 2 * CV_G, PL0 = DN0 + CV_DN;
;                 if (bx >= fi) convert_items(a, lds, k == 0 ? CV_IN : DN0, k == 0 ? DN0 : PL0, k == 0 ? PL0 : CV_PER_LAYER, k == 0 ? CV_PER_LAYER : 2 * CV_PER_LAYER, (bx - fi) * NWAVES + wave, (G - fi) * NWAVES, wave, lane);
.LBB0_374:
	v_readlane_b32 s4, v240, 6
	s_cmp_eq_u32 s4, 0
	s_cbranch_scc1 .Lcv_go
	s_cmp_lg_u32 s4, 4
	s_cbranch_scc1 .LBB0_404
	v_readlane_b32 s4, v240, 4
	v_readlane_b32 s5, v240, 5
	s_andn2_b64 vcc, exec, s[4:5]
	s_cbranch_vccnz .LBB0_404
.Lcv_go:
	s_abs_i32 s4, s3
	v_cvt_f32_u32_e32 v0, s4
	s_sub_i32 s5, 0, s4
	v_rcp_iflag_f32_e32 v0, v0
	s_nop 0
	v_mul_f32_e32 v0, 0x4f7ffffe, v0
	v_cvt_u32_f32_e32 v0, v0
	s_nop 0
	v_readfirstlane_b32 s7, v0
	s_mul_i32 s5, s5, s7
	s_mul_hi_u32 s5, s7, s5
	s_add_i32 s7, s7, s5
	s_mul_hi_u32 s5, s21, s7
	s_mul_i32 s5, s5, s4
	s_sub_i32 s5, s21, s5
	s_sub_i32 s7, s5, s4
	s_cmp_ge_u32 s5, s4
	s_cselect_b32 s5, s7, s5
	s_sub_i32 s7, s5, s4
	s_cmp_ge_u32 s5, s4
	s_cselect_b32 s4, s7, s5
	s_cmp_lt_i32 s2, s4
	s_cbranch_scc1 .LBB0_404
	s_sub_i32 s5, s2, s4
	s_lshl_b32 s5, s5, 3
	v_readlane_b32 s7, v240, 1
	s_add_i32 s7, s5, s7
	s_movk_i32 s14, 0x2680
	s_movk_i32 s15, 0x1f00
	s_movk_i32 s17, 0x1040
	s_movk_i32 s18, 0x2e00
	s_and_b64 vcc, exec, s[36:37]
	s_cbranch_vccz .Lcv_consts_done
	s_movk_i32 s14, 0x1a40
	s_movk_i32 s15, 0x500
	s_movk_i32 s17, 0x1a00
	s_movk_i32 s18, 0x1000
	v_readlane_b32 s8, v240, 4
	v_readlane_b32 s9, v240, 5
	s_and_b64 vcc, exec, s[8:9]
	s_cbranch_vccnz .Lcv_consts_done
	s_movk_i32 s14, 0xf00
	s_movk_i32 s15, 0x2f40
	s_movk_i32 s17, 0xf00
.Lcv_consts_done:
	s_cmp_ge_i32 s7, s14
	s_cbranch_scc1 .LBB0_404
	s_sub_i32 s4, s3, s4
	s_lshl_b32 s16, s4, 3
	v_readlane_b32 s4, v240, 1
	v_lshlrev_b32_e32 v0, 2, v206
	s_mulk_i32 s4, 0x4100
	v_lshrrev_b32_e32 v3, 4, v206
	v_and_b32_e32 v2, 60, v0
	s_add_i32 s8, s4, 0
	v_lshlrev_b32_e32 v0, 2, v2
	v_mul_u32_u24_e32 v4, 0x104, v3
	v_add3_u32 v5, s8, v0, v4
	v_lshlrev_b32_e32 v0, 3, v206
	v_lshrrev_b32_e32 v8, 3, v206
	v_and_b32_e32 v4, 56, v0
	v_mul_u32_u24_e32 v0, 0x104, v4
	v_lshlrev_b32_e32 v6, 2, v8
	v_add3_u32 v9, s8, v0, v6
	v_or_b32_e32 v10, 8, v8
	v_or_b32_e32 v11, 16, v8
	v_or_b32_e32 v12, 24, v8
	v_or_b32_e32 v13, 32, v8
	v_or_b32_e32 v14, 40, v8
	v_or_b32_e32 v15, 48, v8
	v_or_b32_e32 v16, 56, v8
	s_branch .LBB0_384
